# P1: one static priority raise for the block with blockIdx bit 8 set (per-chain setprio toggles removed)
# baseline (speedup 1.0000x reference)
; DI int TID() { int t = threadIdx.x; asm volatile("" : "+v"(t)); return t; }
; DI void phase1(const Params& p, int l, char* lds) {
;   const int tid = TID(), lane = tid & 63, w = tid >> 6, wm = w >> 1, wn = w & 1, r = lane & 31, h = lane >> 5;
;   for (int tile = blockIdx.x; tile < 128 * 51; tile += gridDim.x) {
;     const int grp = tile / (32 * 51), rem = tile % (32 * 51);
;     const int nt = rem >> 5, mt = grp * 32 + (rem & 31);
;     f32x16 acc[2][2];
;     zero_acc(acc);
;     gemm_mainloop(p.xn + (size_t)mt * 128 * 1024, 1024, WINT(l) + (size_t)nt * 128 * 1024, 1024, 1024, lds, acc);
;     {
;       const int col0 = nt * 128 + wn * 64;
;       const float* gain = nullptr;
;       float sc = 1.f;
;       if (col0 < 512) { gain = p.qn_a + l * 64; sc = QSCALE; }
;       else if (col0 < 1024) { gain = p.kn_a + l * 64; }
;       else if (col0 >= QC && col0 < QC + 512) { gain = p.qn_c + l * 64; sc = QSCALE; }
;       else if ((col0 >= KSC && col0 < KSC + 128) || (col0 >= KWC && col0 < KWC + 128)) { gain = p.kn_c + l * 64; }
.LBB0_216:
	s_or_b64 exec, exec, s[0:1]
	v_readlane_b32 s0, v252, 59
	v_readlane_b32 s1, v252, 60
	s_lshl_b32 s2, s78, 6
	v_mov_b32_e32 v0, v209
	s_and_b64 vcc, exec, s[0:1]
	s_waitcnt lgkmcnt(0)
	s_barrier
	s_cbranch_vccz .LBB0_233
	v_readlane_b32 s0, v253, 1
	v_readlane_b32 s1, v253, 2
	v_lshlrev_b32_e32 v66, 4, v209
	s_nop 4
	global_store_dwordx4 v66, v[168:171], s[0:1]
	v_add_u32_e32 v66, 0x1000, v66
	global_store_dwordx4 v66, v[172:175], s[0:1]
	v_add_u32_e32 v66, 0x1000, v66
	global_store_dwordx4 v66, v[176:179], s[0:1]
	v_add_u32_e32 v66, 0x1000, v66
	global_store_dwordx4 v66, v[180:183], s[0:1]
	v_add_u32_e32 v66, 0x1000, v66
	global_store_dwordx4 v66, v[184:187], s[0:1]
	v_add_u32_e32 v66, 0x1000, v66
	s_mul_i32 s18, s78, 0x660000
	v_readlane_b32 s80, v253, 12
	s_lshl_b64 s[0:1], s[18:19], 1
	v_readlane_b32 s90, v253, 22
	s_mov_b32 s3, s19
	v_readlane_b32 s91, v253, 23
	s_add_u32 s20, s90, s0
	s_addc_u32 s21, s91, s1
	s_lshl_b64 s[0:1], s[2:3], 2
	s_add_u32 s4, s72, s0
	s_addc_u32 s5, s73, s1
	s_add_u32 s6, s70, s0
	v_readlane_b32 s36, v251, 2
	s_addc_u32 s7, s71, s1
	v_readlane_b32 s46, v251, 12
	v_readlane_b32 s47, v251, 13
	s_add_u32 s8, s46, s0
	v_readlane_b32 s44, v251, 10
	s_addc_u32 s9, s47, s1
	s_add_u32 s10, s44, s0
	v_lshlrev_b32_e32 v2, 2, v0
	s_movk_i32 s0, 0x80
	v_bfrev_b32_e32 v3, 0.5
	v_bitop3_b32 v154, v2, s0, v3 bitop3:0x6c
	v_lshrrev_b32_e32 v2, 3, v0
	v_readlane_b32 s45, v251, 11
	v_and_b32_e32 v130, 4, v2
	v_ashrrev_i32_e32 v2, 1, v0
	s_addc_u32 s11, s45, s1
	v_and_b32_e32 v2, 0xffffffc0, v2
	v_readlane_b32 s0, v253, 36
	s_mov_b32 s25, s19
	v_readlane_b32 s88, v253, 20
	v_readlane_b32 s89, v253, 21
	v_and_b32_e32 v131, 64, v0
	v_ashrrev_i32_e32 v133, 31, v2
	v_and_or_b32 v132, v0, 31, v2
	s_mov_b32 s3, s0
	v_readlane_b32 s81, v253, 13
	v_readlane_b32 s82, v253, 14
	v_readlane_b32 s83, v253, 15
	v_readlane_b32 s84, v253, 16
	v_readlane_b32 s85, v253, 17
	v_readlane_b32 s86, v253, 18
	v_readlane_b32 s87, v253, 19
	v_readlane_b32 s92, v253, 24
	v_readlane_b32 s93, v253, 25
	v_readlane_b32 s94, v253, 26
	v_readlane_b32 s95, v253, 27
	v_readlane_b32 s37, v251, 3
	v_readlane_b32 s38, v251, 4
	v_readlane_b32 s39, v251, 5
	v_readlane_b32 s40, v251, 6
	v_readlane_b32 s41, v251, 7
	v_readlane_b32 s42, v251, 8
	v_readlane_b32 s43, v251, 9
	v_readlane_b32 s48, v251, 14
	v_readlane_b32 s49, v251, 15
	v_readlane_b32 s50, v251, 16
	v_readlane_b32 s51, v251, 17
	v_readlane_b32 s1, v253, 37
	v_readlane_b32 s1, v253, 36
	s_nop 0
	s_bitcmp1_b32 s1, 8
	s_cbranch_scc0 .Lp1_lowprio
	s_setprio 3
.Lp1_lowprio:
	s_branch .LBB0_219

; DI int TID() { int t = threadIdx.x; asm volatile("" : "+v"(t)); return t; }
; #define GEMM_GLOAD(P, kt_) { GEMM_GL1(P, 0, kt_) GEMM_GL1(P, 1, kt_) GEMM_GL1(P, 2, kt_) GEMM_GL1(P, 3, kt_) }
; #define GEMM_LSTORE(P, buf_) { GEMM_LS1(P, 0, buf_) GEMM_LS1(P, 1, buf_) GEMM_LS1(P, 2, buf_) GEMM_LS1(P, 3, buf_) }
; template <bool DEEP>
; DI void gemm_mainloop_t(const u16* __restrict__ Ag, int lda, const u16* __restrict__ Bg, int ldb, int K, char* ldsraw,
;                         f32x16 (&acc)[2][2], int akstep) {
;   const int tid = TID(), lane = tid & 63, w = tid >> 6, wm = w >> 1, wn = w & 1, r = lane & 31, h = lane >> 5;
;   u16* As = (u16*)ldsraw;
;   u16* Bs = As + 2 * 128 * LDT;
;   uint4 xa0, xa1, xa2, xa3, xb0, xb1, xb2, xb3;
;   const int nk = K >> 6;
;   const int row0 = tid >> 3, cc = tid & 7;
;   if (DEEP) {
;     uint4 ya0, ya1, ya2, ya3, yb0, yb1, yb2, yb3;
;     GEMM_GLOAD(x, 0);
;     GEMM_GLOAD(y, 1);
;     GEMM_LSTORE(x, 0);
;     __syncthreads();
;     for (int kt = 0; kt < nk; kt += 2) {
;       if (kt + 2 < nk) GEMM_GLOAD(x, kt + 2);
;       GEMM_COMPUTE(0);
;       GEMM_LSTORE(y, 1);
;       __syncthreads();
;       if (kt + 3 < nk) GEMM_GLOAD(y, kt + 3);
;       GEMM_COMPUTE(1);
;       if (kt + 2 < nk) GEMM_LSTORE(x, 0);
;       __syncthreads();
;     }
;   } else {
;     GEMM_GLOAD(x, 0);
;     GEMM_LSTORE(x, 0);
;     __syncthreads();
; DI void phase1(const Params& p, int l, char* lds) {
;     ...
;   for (int tile = blockIdx.x; tile < 128 * 51; tile += gridDim.x) {
;     const int grp = tile / (32 * 51), rem = tile % (32 * 51);
;     const int nt = rem >> 5, mt = grp * 32 + (rem & 31);
.LBB0_219:
	s_mul_hi_i32 s0, s3, 0xa0a0a0a1
	s_add_i32 s0, s0, s3
	s_lshr_b32 s1, s0, 31
	s_ashr_i32 s0, s0, 10
	s_add_i32 s1, s0, s1
	s_mul_i32 s0, s1, 0xfffff9a0
	s_add_i32 s18, s3, s0
	s_lshl_b32 s1, s1, 5
	s_and_b32 s12, s18, 31
	s_or_b32 s12, s1, s12
	s_ashr_i32 s13, s12, 31
	s_ashr_i32 s0, s18, 5
	s_lshl_b64 s[14:15], s[12:13], 18
	s_waitcnt vmcnt(31)
	s_add_u32 s14, s88, s14
	s_addc_u32 s15, s89, s15
	s_ashr_i32 s1, s0, 31
	s_lshl_b64 s[16:17], s[0:1], 18
	s_add_u32 s16, s20, s16
	s_addc_u32 s17, s21, s17
	v_lshrrev_b32_e32 v146, 3, v209
	v_and_b32_e32 v147, 7, v209
	v_lshlrev_b32_e32 v147, 4, v147
	v_mov_b32_e32 v148, v146
	v_mul_u32_u24_e32 v134, 0x800, v148
	v_add_u32_e32 v134, v134, v147
	v_mul_u32_u24_e32 v138, 0x800, v148
	v_add_u32_e32 v138, v138, v147
	v_add_u32_e32 v148, 32, v146
	v_mul_u32_u24_e32 v135, 0x800, v148
	v_add_u32_e32 v135, v135, v147
	v_mul_u32_u24_e32 v139, 0x800, v148
	v_add_u32_e32 v139, v139, v147
	v_add_u32_e32 v148, 64, v146
	v_mul_u32_u24_e32 v136, 0x800, v148
	v_add_u32_e32 v136, v136, v147
	v_mul_u32_u24_e32 v140, 0x800, v148
	v_add_u32_e32 v140, v140, v147
	v_add_u32_e32 v148, 96, v146
	v_mul_u32_u24_e32 v137, 0x800, v148
	v_add_u32_e32 v137, v137, v147
	v_mul_u32_u24_e32 v141, 0x800, v148
	v_add_u32_e32 v141, v141, v147
	v_mul_u32_u24_e32 v142, 0x90, v146
	v_add_u32_e32 v142, v142, v147
	v_add_u32_e32 v143, 0x1200, v142
	v_and_b32_e32 v146, 31, v209
	v_bfe_u32 v147, v209, 5, 1
	v_lshlrev_b32_e32 v147, 4, v147
	v_bfe_u32 v148, v209, 7, 1
	v_lshl_add_u32 v148, v148, 6, v146
	v_mul_u32_u24_e32 v144, 0x90, v148
	v_add_u32_e32 v144, v144, v147
	v_bfe_u32 v148, v209, 6, 1
	v_lshl_add_u32 v148, v148, 6, v146
	v_mul_u32_u24_e32 v145, 0x90, v148
	v_add_u32_e32 v145, v145, v147
	global_load_dwordx4 v[66:69], v134, s[14:15]
	global_load_dwordx4 v[70:73], v138, s[16:17]
	global_load_dwordx4 v[74:77], v135, s[14:15]
	global_load_dwordx4 v[78:81], v139, s[16:17]
	global_load_dwordx4 v[82:85], v136, s[14:15]
	global_load_dwordx4 v[86:89], v140, s[16:17]
	global_load_dwordx4 v[90:93], v137, s[14:15]
	global_load_dwordx4 v[94:97], v141, s[16:17]
	global_load_dwordx4 v[98:101], v134, s[14:15] offset:128
	global_load_dwordx4 v[102:105], v138, s[16:17] offset:128
	global_load_dwordx4 v[106:109], v135, s[14:15] offset:128
	global_load_dwordx4 v[110:113], v139, s[16:17] offset:128
	global_load_dwordx4 v[114:117], v136, s[14:15] offset:128
	global_load_dwordx4 v[118:121], v140, s[16:17] offset:128
	global_load_dwordx4 v[122:125], v137, s[14:15] offset:128
	global_load_dwordx4 v[126:129], v141, s[16:17] offset:128
	s_waitcnt vmcnt(15)
	ds_write_b128 v142, v[66:69]
	s_waitcnt vmcnt(14)
	ds_write_b128 v142, v[70:73] offset:36864
	s_waitcnt vmcnt(13)
	ds_write_b128 v142, v[74:77] offset:4608
	s_waitcnt vmcnt(12)
	ds_write_b128 v142, v[78:81] offset:41472
	s_waitcnt vmcnt(11)
	ds_write_b128 v142, v[82:85] offset:9216
	s_waitcnt vmcnt(10)
	ds_write_b128 v142, v[86:89] offset:46080
	s_waitcnt vmcnt(9)
	ds_write_b128 v142, v[90:93] offset:13824
	s_waitcnt vmcnt(8)
	ds_write_b128 v142, v[94:97] offset:50688
	s_waitcnt lgkmcnt(0)
	s_barrier
	ds_read_b128 v[156:159], v145 offset:36864
	ds_read_b128 v[160:163], v144
	ds_read_b128 v[164:167], v145 offset:41472
	ds_read_b128 v[168:171], v144 offset:4608
	s_waitcnt lgkmcnt(2)
	v_mfma_f32_32x32x16_f16 v[50:65], v[156:159], v[160:163], 0
	global_load_dwordx4 v[66:69], v134, s[14:15] offset:256
	s_waitcnt lgkmcnt(1)
	v_mfma_f32_32x32x16_f16 v[34:49], v[164:167], v[160:163], 0
	ds_read_b128 v[160:163], v144 offset:32
	s_waitcnt vmcnt(8)
	ds_write_b128 v142, v[98:101] offset:18432
	s_waitcnt lgkmcnt(2)
	v_mfma_f32_32x32x16_f16 v[18:33], v[156:159], v[168:171], 0
	ds_read_b128 v[156:159], v145 offset:36896
	global_load_dwordx4 v[70:73], v138, s[16:17] offset:256
	v_mfma_f32_32x32x16_f16 v[2:17], v[164:167], v[168:171], 0
	ds_read_b128 v[164:167], v145 offset:41504
	ds_read_b128 v[168:171], v144 offset:4640
	s_waitcnt vmcnt(8)
	ds_write_b128 v142, v[102:105] offset:55296
	s_waitcnt lgkmcnt(3)
	v_mfma_f32_32x32x16_f16 v[50:65], v[156:159], v[160:163], v[50:65]
	global_load_dwordx4 v[74:77], v135, s[14:15] offset:256
	s_waitcnt lgkmcnt(2)
	v_mfma_f32_32x32x16_f16 v[34:49], v[164:167], v[160:163], v[34:49]
	ds_read_b128 v[160:163], v144 offset:64
	s_waitcnt vmcnt(8)
	ds_write_b128 v142, v[106:109] offset:23040
	s_waitcnt lgkmcnt(3)
	v_mfma_f32_32x32x16_f16 v[18:33], v[156:159], v[168:171], v[18:33]
	ds_read_b128 v[156:159], v145 offset:36928
	global_load_dwordx4 v[78:81], v139, s[16:17] offset:256
	v_mfma_f32_32x32x16_f16 v[2:17], v[164:167], v[168:171], v[2:17]
	ds_read_b128 v[164:167], v145 offset:41536
	ds_read_b128 v[168:171], v144 offset:4672
	s_waitcnt vmcnt(8)
	ds_write_b128 v142, v[110:113] offset:59904
	s_waitcnt lgkmcnt(3)
	v_mfma_f32_32x32x16_f16 v[50:65], v[156:159], v[160:163], v[50:65]
	global_load_dwordx4 v[82:85], v136, s[14:15] offset:256
	s_waitcnt lgkmcnt(2)
	v_mfma_f32_32x32x16_f16 v[34:49], v[164:167], v[160:163], v[34:49]
	ds_read_b128 v[160:163], v144 offset:96
	s_waitcnt vmcnt(8)
	ds_write_b128 v142, v[114:117] offset:27648
	s_waitcnt lgkmcnt(3)
	v_mfma_f32_32x32x16_f16 v[18:33], v[156:159], v[168:171], v[18:33]
	ds_read_b128 v[156:159], v145 offset:36960
	global_load_dwordx4 v[86:89], v140, s[16:17] offset:256
	v_mfma_f32_32x32x16_f16 v[2:17], v[164:167], v[168:171], v[2:17]
	ds_read_b128 v[164:167], v145 offset:41568
	ds_read_b128 v[168:171], v144 offset:4704
	s_waitcnt vmcnt(8)
	ds_write_b128 v142, v[118:121] offset:64512
	s_waitcnt lgkmcnt(3)
	v_mfma_f32_32x32x16_f16 v[50:65], v[156:159], v[160:163], v[50:65]
	global_load_dwordx4 v[90:93], v137, s[14:15] offset:256
	s_waitcnt lgkmcnt(2)
	v_mfma_f32_32x32x16_f16 v[34:49], v[164:167], v[160:163], v[34:49]
	s_waitcnt vmcnt(8)
	ds_write_b128 v142, v[122:125] offset:32256
	s_waitcnt lgkmcnt(2)
	v_mfma_f32_32x32x16_f16 v[18:33], v[156:159], v[168:171], v[18:33]
	global_load_dwordx4 v[94:97], v141, s[16:17] offset:256
	v_mfma_f32_32x32x16_f16 v[2:17], v[164:167], v[168:171], v[2:17]
	s_waitcnt vmcnt(8)
	ds_write_b128 v143, v[126:129] offset:64512
	s_waitcnt lgkmcnt(0)
	s_barrier
; #define GEMM_GLOAD(P, kt_) { GEMM_GL1(P, 0, kt_) GEMM_GL1(P, 1, kt_) GEMM_GL1(P, 2, kt_) GEMM_GL1(P, 3, kt_) }
; #define GEMM_LSTORE(P, buf_) { GEMM_LS1(P, 0, buf_) GEMM_LS1(P, 1, buf_) GEMM_LS1(P, 2, buf_) GEMM_LS1(P, 3, buf_) }
; template <bool DEEP>
; DI void gemm_mainloop_t(const u16* __restrict__ Ag, int lda, const u16* __restrict__ Bg, int ldb, int K, char* ldsraw,
;                         f32x16 (&acc)[2][2], int akstep) {
;     ...
;     for (int kt = 0; kt < nk; kt += 2) {
;       if (kt + 2 < nk) GEMM_GLOAD(x, kt + 2);
;       GEMM_COMPUTE(0);
;       GEMM_LSTORE(y, 1);
;       __syncthreads();
;       if (kt + 3 < nk) GEMM_GLOAD(y, kt + 3);
;       GEMM_COMPUTE(1);
;       if (kt + 2 < nk) GEMM_LSTORE(x, 0);
;       __syncthreads();
;     }
	ds_read_b128 v[156:159], v145 offset:55296
	ds_read_b128 v[160:163], v144 offset:18432
	ds_read_b128 v[164:167], v145 offset:59904
	ds_read_b128 v[168:171], v144 offset:23040
	s_waitcnt lgkmcnt(2)
	v_mfma_f32_32x32x16_f16 v[50:65], v[156:159], v[160:163], v[50:65]
	global_load_dwordx4 v[98:101], v134, s[14:15] offset:384
	s_waitcnt lgkmcnt(1)
	v_mfma_f32_32x32x16_f16 v[34:49], v[164:167], v[160:163], v[34:49]
	ds_read_b128 v[160:163], v144 offset:18464
	s_waitcnt vmcnt(8)
	ds_write_b128 v142, v[66:69]
	s_waitcnt lgkmcnt(2)
	v_mfma_f32_32x32x16_f16 v[18:33], v[156:159], v[168:171], v[18:33]
	ds_read_b128 v[156:159], v145 offset:55328
	global_load_dwordx4 v[102:105], v138, s[16:17] offset:384
	v_mfma_f32_32x32x16_f16 v[2:17], v[164:167], v[168:171], v[2:17]
	ds_read_b128 v[164:167], v145 offset:59936
	ds_read_b128 v[168:171], v144 offset:23072
	s_waitcnt vmcnt(8)
	ds_write_b128 v142, v[70:73] offset:36864
	s_waitcnt lgkmcnt(3)
	v_mfma_f32_32x32x16_f16 v[50:65], v[156:159], v[160:163], v[50:65]
	global_load_dwordx4 v[106:109], v135, s[14:15] offset:384
	s_waitcnt lgkmcnt(2)
	v_mfma_f32_32x32x16_f16 v[34:49], v[164:167], v[160:163], v[34:49]
	ds_read_b128 v[160:163], v144 offset:18496
	s_waitcnt vmcnt(8)
	ds_write_b128 v142, v[74:77] offset:4608
	s_waitcnt lgkmcnt(3)
	v_mfma_f32_32x32x16_f16 v[18:33], v[156:159], v[168:171], v[18:33]
	ds_read_b128 v[156:159], v145 offset:55360
	global_load_dwordx4 v[110:113], v139, s[16:17] offset:384
	v_mfma_f32_32x32x16_f16 v[2:17], v[164:167], v[168:171], v[2:17]
	ds_read_b128 v[164:167], v145 offset:59968
	ds_read_b128 v[168:171], v144 offset:23104
	s_waitcnt vmcnt(8)
	ds_write_b128 v142, v[78:81] offset:41472
	s_waitcnt lgkmcnt(3)
	v_mfma_f32_32x32x16_f16 v[50:65], v[156:159], v[160:163], v[50:65]
	global_load_dwordx4 v[114:117], v136, s[14:15] offset:384
	s_waitcnt lgkmcnt(2)
	v_mfma_f32_32x32x16_f16 v[34:49], v[164:167], v[160:163], v[34:49]
	ds_read_b128 v[160:163], v144 offset:18528
	s_waitcnt vmcnt(8)
	ds_write_b128 v142, v[82:85] offset:9216
	s_waitcnt lgkmcnt(3)
	v_mfma_f32_32x32x16_f16 v[18:33], v[156:159], v[168:171], v[18:33]
	ds_read_b128 v[156:159], v145 offset:55392
	global_load_dwordx4 v[118:121], v140, s[16:17] offset:384
	v_mfma_f32_32x32x16_f16 v[2:17], v[164:167], v[168:171], v[2:17]
	ds_read_b128 v[164:167], v145 offset:60000
	ds_read_b128 v[168:171], v144 offset:23136
	s_waitcnt vmcnt(8)
	ds_write_b128 v142, v[86:89] offset:46080
	s_waitcnt lgkmcnt(3)
	v_mfma_f32_32x32x16_f16 v[50:65], v[156:159], v[160:163], v[50:65]
	global_load_dwordx4 v[122:125], v137, s[14:15] offset:384
	s_waitcnt lgkmcnt(2)
	v_mfma_f32_32x32x16_f16 v[34:49], v[164:167], v[160:163], v[34:49]
	s_waitcnt vmcnt(8)
	ds_write_b128 v142, v[90:93] offset:13824
	s_waitcnt lgkmcnt(2)
	v_mfma_f32_32x32x16_f16 v[18:33], v[156:159], v[168:171], v[18:33]
	global_load_dwordx4 v[126:129], v141, s[16:17] offset:384
	v_mfma_f32_32x32x16_f16 v[2:17], v[164:167], v[168:171], v[2:17]
	s_waitcnt vmcnt(8)
	ds_write_b128 v142, v[94:97] offset:50688
	s_waitcnt lgkmcnt(0)
	s_barrier
	ds_read_b128 v[156:159], v145 offset:36864
	ds_read_b128 v[160:163], v144
	ds_read_b128 v[164:167], v145 offset:41472
	ds_read_b128 v[168:171], v144 offset:4608
	s_waitcnt lgkmcnt(2)
	v_mfma_f32_32x32x16_f16 v[50:65], v[156:159], v[160:163], v[50:65]
	global_load_dwordx4 v[66:69], v134, s[14:15] offset:512
	s_waitcnt lgkmcnt(1)
	v_mfma_f32_32x32x16_f16 v[34:49], v[164:167], v[160:163], v[34:49]
	ds_read_b128 v[160:163], v144 offset:32
	s_waitcnt vmcnt(8)
	ds_write_b128 v142, v[98:101] offset:18432
	s_waitcnt lgkmcnt(2)
	v_mfma_f32_32x32x16_f16 v[18:33], v[156:159], v[168:171], v[18:33]
	ds_read_b128 v[156:159], v145 offset:36896
	global_load_dwordx4 v[70:73], v138, s[16:17] offset:512
	v_mfma_f32_32x32x16_f16 v[2:17], v[164:167], v[168:171], v[2:17]
	ds_read_b128 v[164:167], v145 offset:41504
	ds_read_b128 v[168:171], v144 offset:4640
	s_waitcnt vmcnt(8)
	ds_write_b128 v142, v[102:105] offset:55296
	s_waitcnt lgkmcnt(3)
	v_mfma_f32_32x32x16_f16 v[50:65], v[156:159], v[160:163], v[50:65]
	global_load_dwordx4 v[74:77], v135, s[14:15] offset:512
	s_waitcnt lgkmcnt(2)
	v_mfma_f32_32x32x16_f16 v[34:49], v[164:167], v[160:163], v[34:49]
	ds_read_b128 v[160:163], v144 offset:64
	s_waitcnt vmcnt(8)
	ds_write_b128 v142, v[106:109] offset:23040
	s_waitcnt lgkmcnt(3)
	v_mfma_f32_32x32x16_f16 v[18:33], v[156:159], v[168:171], v[18:33]
	ds_read_b128 v[156:159], v145 offset:36928
	global_load_dwordx4 v[78:81], v139, s[16:17] offset:512
	v_mfma_f32_32x32x16_f16 v[2:17], v[164:167], v[168:171], v[2:17]
	ds_read_b128 v[164:167], v145 offset:41536
	ds_read_b128 v[168:171], v144 offset:4672
	s_waitcnt vmcnt(8)
	ds_write_b128 v142, v[110:113] offset:59904
	s_waitcnt lgkmcnt(3)
	v_mfma_f32_32x32x16_f16 v[50:65], v[156:159], v[160:163], v[50:65]
	global_load_dwordx4 v[82:85], v136, s[14:15] offset:512
	s_waitcnt lgkmcnt(2)
	v_mfma_f32_32x32x16_f16 v[34:49], v[164:167], v[160:163], v[34:49]
	ds_read_b128 v[160:163], v144 offset:96
	s_waitcnt vmcnt(8)
	ds_write_b128 v142, v[114:117] offset:27648
	s_waitcnt lgkmcnt(3)
	v_mfma_f32_32x32x16_f16 v[18:33], v[156:159], v[168:171], v[18:33]
	ds_read_b128 v[156:159], v145 offset:36960
	global_load_dwordx4 v[86:89], v140, s[16:17] offset:512
	v_mfma_f32_32x32x16_f16 v[2:17], v[164:167], v[168:171], v[2:17]
	ds_read_b128 v[164:167], v145 offset:41568
	ds_read_b128 v[168:171], v144 offset:4704
	s_waitcnt vmcnt(8)
	ds_write_b128 v142, v[118:121] offset:64512
	s_waitcnt lgkmcnt(3)
	v_mfma_f32_32x32x16_f16 v[50:65], v[156:159], v[160:163], v[50:65]
	global_load_dwordx4 v[90:93], v137, s[14:15] offset:512
	s_waitcnt lgkmcnt(2)
	v_mfma_f32_32x32x16_f16 v[34:49], v[164:167], v[160:163], v[34:49]
	s_waitcnt vmcnt(8)
	ds_write_b128 v142, v[122:125] offset:32256
	s_waitcnt lgkmcnt(2)
	v_mfma_f32_32x32x16_f16 v[18:33], v[156:159], v[168:171], v[18:33]
	global_load_dwordx4 v[94:97], v141, s[16:17] offset:512
	v_mfma_f32_32x32x16_f16 v[2:17], v[164:167], v[168:171], v[2:17]
	s_waitcnt vmcnt(8)
	ds_write_b128 v143, v[126:129] offset:64512
	s_waitcnt lgkmcnt(0)
	s_barrier
; #define GEMM_GLOAD(P, kt_) { GEMM_GL1(P, 0, kt_) GEMM_GL1(P, 1, kt_) GEMM_GL1(P, 2, kt_) GEMM_GL1(P, 3, kt_) }
; #define GEMM_LSTORE(P, buf_) { GEMM_LS1(P, 0, buf_) GEMM_LS1(P, 1, buf_) GEMM_LS1(P, 2, buf_) GEMM_LS1(P, 3, buf_) }
; template <bool DEEP>
; DI void gemm_mainloop_t(const u16* __restrict__ Ag, int lda, const u16* __restrict__ Bg, int ldb, int K, char* ldsraw,
;                         f32x16 (&acc)[2][2], int akstep) {
;     ...
;     for (int kt = 0; kt < nk; kt += 2) {
;       if (kt + 2 < nk) GEMM_GLOAD(x, kt + 2);
;       GEMM_COMPUTE(0);
;       GEMM_LSTORE(y, 1);
;       __syncthreads();
;       if (kt + 3 < nk) GEMM_GLOAD(y, kt + 3);
;       GEMM_COMPUTE(1);
;       if (kt + 2 < nk) GEMM_LSTORE(x, 0);
;       __syncthreads();
;     }
	ds_read_b128 v[156:159], v145 offset:55296
	ds_read_b128 v[160:163], v144 offset:18432
	ds_read_b128 v[164:167], v145 offset:59904
	ds_read_b128 v[168:171], v144 offset:23040
	s_waitcnt lgkmcnt(2)
	v_mfma_f32_32x32x16_f16 v[50:65], v[156:159], v[160:163], v[50:65]
	global_load_dwordx4 v[98:101], v134, s[14:15] offset:640
	s_waitcnt lgkmcnt(1)
	v_mfma_f32_32x32x16_f16 v[34:49], v[164:167], v[160:163], v[34:49]
	ds_read_b128 v[160:163], v144 offset:18464
	s_waitcnt vmcnt(8)
	ds_write_b128 v142, v[66:69]
	s_waitcnt lgkmcnt(2)
	v_mfma_f32_32x32x16_f16 v[18:33], v[156:159], v[168:171], v[18:33]
	ds_read_b128 v[156:159], v145 offset:55328
	global_load_dwordx4 v[102:105], v138, s[16:17] offset:640
	v_mfma_f32_32x32x16_f16 v[2:17], v[164:167], v[168:171], v[2:17]
	ds_read_b128 v[164:167], v145 offset:59936
	ds_read_b128 v[168:171], v144 offset:23072
	s_waitcnt vmcnt(8)
	ds_write_b128 v142, v[70:73] offset:36864
	s_waitcnt lgkmcnt(3)
	v_mfma_f32_32x32x16_f16 v[50:65], v[156:159], v[160:163], v[50:65]
	global_load_dwordx4 v[106:109], v135, s[14:15] offset:640
	s_waitcnt lgkmcnt(2)
	v_mfma_f32_32x32x16_f16 v[34:49], v[164:167], v[160:163], v[34:49]
	ds_read_b128 v[160:163], v144 offset:18496
	s_waitcnt vmcnt(8)
	ds_write_b128 v142, v[74:77] offset:4608
	s_waitcnt lgkmcnt(3)
	v_mfma_f32_32x32x16_f16 v[18:33], v[156:159], v[168:171], v[18:33]
	ds_read_b128 v[156:159], v145 offset:55360
	global_load_dwordx4 v[110:113], v139, s[16:17] offset:640
	v_mfma_f32_32x32x16_f16 v[2:17], v[164:167], v[168:171], v[2:17]
	ds_read_b128 v[164:167], v145 offset:59968
	ds_read_b128 v[168:171], v144 offset:23104
	s_waitcnt vmcnt(8)
	ds_write_b128 v142, v[78:81] offset:41472
	s_waitcnt lgkmcnt(3)
	v_mfma_f32_32x32x16_f16 v[50:65], v[156:159], v[160:163], v[50:65]
	global_load_dwordx4 v[114:117], v136, s[14:15] offset:640
	s_waitcnt lgkmcnt(2)
	v_mfma_f32_32x32x16_f16 v[34:49], v[164:167], v[160:163], v[34:49]
	ds_read_b128 v[160:163], v144 offset:18528
	s_waitcnt vmcnt(8)
	ds_write_b128 v142, v[82:85] offset:9216
	s_waitcnt lgkmcnt(3)
	v_mfma_f32_32x32x16_f16 v[18:33], v[156:159], v[168:171], v[18:33]
	ds_read_b128 v[156:159], v145 offset:55392
	global_load_dwordx4 v[118:121], v140, s[16:17] offset:640
	v_mfma_f32_32x32x16_f16 v[2:17], v[164:167], v[168:171], v[2:17]
	ds_read_b128 v[164:167], v145 offset:60000
	ds_read_b128 v[168:171], v144 offset:23136
	s_waitcnt vmcnt(8)
	ds_write_b128 v142, v[86:89] offset:46080
	s_waitcnt lgkmcnt(3)
	v_mfma_f32_32x32x16_f16 v[50:65], v[156:159], v[160:163], v[50:65]
	global_load_dwordx4 v[122:125], v137, s[14:15] offset:640
	s_waitcnt lgkmcnt(2)
	v_mfma_f32_32x32x16_f16 v[34:49], v[164:167], v[160:163], v[34:49]
	s_waitcnt vmcnt(8)
	ds_write_b128 v142, v[90:93] offset:13824
	s_waitcnt lgkmcnt(2)
	v_mfma_f32_32x32x16_f16 v[18:33], v[156:159], v[168:171], v[18:33]
	global_load_dwordx4 v[126:129], v141, s[16:17] offset:640
	v_mfma_f32_32x32x16_f16 v[2:17], v[164:167], v[168:171], v[2:17]
	s_waitcnt vmcnt(8)
	ds_write_b128 v142, v[94:97] offset:50688
	s_waitcnt lgkmcnt(0)
	s_barrier
	ds_read_b128 v[156:159], v145 offset:36864
	ds_read_b128 v[160:163], v144
	ds_read_b128 v[164:167], v145 offset:41472
	ds_read_b128 v[168:171], v144 offset:4608
	s_waitcnt lgkmcnt(2)
	v_mfma_f32_32x32x16_f16 v[50:65], v[156:159], v[160:163], v[50:65]
	global_load_dwordx4 v[66:69], v134, s[14:15] offset:768
	s_waitcnt lgkmcnt(1)
	v_mfma_f32_32x32x16_f16 v[34:49], v[164:167], v[160:163], v[34:49]
	ds_read_b128 v[160:163], v144 offset:32
	s_waitcnt vmcnt(8)
	ds_write_b128 v142, v[98:101] offset:18432
	s_waitcnt lgkmcnt(2)
	v_mfma_f32_32x32x16_f16 v[18:33], v[156:159], v[168:171], v[18:33]
	ds_read_b128 v[156:159], v145 offset:36896
	global_load_dwordx4 v[70:73], v138, s[16:17] offset:768
	v_mfma_f32_32x32x16_f16 v[2:17], v[164:167], v[168:171], v[2:17]
	ds_read_b128 v[164:167], v145 offset:41504
	ds_read_b128 v[168:171], v144 offset:4640
	s_waitcnt vmcnt(8)
	ds_write_b128 v142, v[102:105] offset:55296
	s_waitcnt lgkmcnt(3)
	v_mfma_f32_32x32x16_f16 v[50:65], v[156:159], v[160:163], v[50:65]
	global_load_dwordx4 v[74:77], v135, s[14:15] offset:768
	s_waitcnt lgkmcnt(2)
	v_mfma_f32_32x32x16_f16 v[34:49], v[164:167], v[160:163], v[34:49]
	ds_read_b128 v[160:163], v144 offset:64
	s_waitcnt vmcnt(8)
	ds_write_b128 v142, v[106:109] offset:23040
	s_waitcnt lgkmcnt(3)
	v_mfma_f32_32x32x16_f16 v[18:33], v[156:159], v[168:171], v[18:33]
	ds_read_b128 v[156:159], v145 offset:36928
	global_load_dwordx4 v[78:81], v139, s[16:17] offset:768
	v_mfma_f32_32x32x16_f16 v[2:17], v[164:167], v[168:171], v[2:17]
	ds_read_b128 v[164:167], v145 offset:41536
	ds_read_b128 v[168:171], v144 offset:4672
	s_waitcnt vmcnt(8)
	ds_write_b128 v142, v[110:113] offset:59904
	s_waitcnt lgkmcnt(3)
	v_mfma_f32_32x32x16_f16 v[50:65], v[156:159], v[160:163], v[50:65]
	global_load_dwordx4 v[82:85], v136, s[14:15] offset:768
	s_waitcnt lgkmcnt(2)
	v_mfma_f32_32x32x16_f16 v[34:49], v[164:167], v[160:163], v[34:49]
	ds_read_b128 v[160:163], v144 offset:96
	s_waitcnt vmcnt(8)
	ds_write_b128 v142, v[114:117] offset:27648
	s_waitcnt lgkmcnt(3)
	v_mfma_f32_32x32x16_f16 v[18:33], v[156:159], v[168:171], v[18:33]
	ds_read_b128 v[156:159], v145 offset:36960
	global_load_dwordx4 v[86:89], v140, s[16:17] offset:768
	v_mfma_f32_32x32x16_f16 v[2:17], v[164:167], v[168:171], v[2:17]
	ds_read_b128 v[164:167], v145 offset:41568
	ds_read_b128 v[168:171], v144 offset:4704
	s_waitcnt vmcnt(8)
	ds_write_b128 v142, v[118:121] offset:64512
	s_waitcnt lgkmcnt(3)
	v_mfma_f32_32x32x16_f16 v[50:65], v[156:159], v[160:163], v[50:65]
	global_load_dwordx4 v[90:93], v137, s[14:15] offset:768
	s_waitcnt lgkmcnt(2)
	v_mfma_f32_32x32x16_f16 v[34:49], v[164:167], v[160:163], v[34:49]
	s_waitcnt vmcnt(8)
	ds_write_b128 v142, v[122:125] offset:32256
	s_waitcnt lgkmcnt(2)
	v_mfma_f32_32x32x16_f16 v[18:33], v[156:159], v[168:171], v[18:33]
	global_load_dwordx4 v[94:97], v141, s[16:17] offset:768
	v_mfma_f32_32x32x16_f16 v[2:17], v[164:167], v[168:171], v[2:17]
	s_waitcnt vmcnt(8)
	ds_write_b128 v143, v[126:129] offset:64512
	s_waitcnt lgkmcnt(0)
	s_barrier
; #define GEMM_GLOAD(P, kt_) { GEMM_GL1(P, 0, kt_) GEMM_GL1(P, 1, kt_) GEMM_GL1(P, 2, kt_) GEMM_GL1(P, 3, kt_) }
; #define GEMM_LSTORE(P, buf_) { GEMM_LS1(P, 0, buf_) GEMM_LS1(P, 1, buf_) GEMM_LS1(P, 2, buf_) GEMM_LS1(P, 3, buf_) }
; template <bool DEEP>
; DI void gemm_mainloop_t(const u16* __restrict__ Ag, int lda, const u16* __restrict__ Bg, int ldb, int K, char* ldsraw,
;                         f32x16 (&acc)[2][2], int akstep) {
;     ...
;     for (int kt = 0; kt < nk; kt += 2) {
;       if (kt + 2 < nk) GEMM_GLOAD(x, kt + 2);
;       GEMM_COMPUTE(0);
;       GEMM_LSTORE(y, 1);
;       __syncthreads();
;       if (kt + 3 < nk) GEMM_GLOAD(y, kt + 3);
;       GEMM_COMPUTE(1);
;       if (kt + 2 < nk) GEMM_LSTORE(x, 0);
;       __syncthreads();
;     }
	ds_read_b128 v[156:159], v145 offset:55296
	ds_read_b128 v[160:163], v144 offset:18432
	ds_read_b128 v[164:167], v145 offset:59904
	ds_read_b128 v[168:171], v144 offset:23040
	s_waitcnt lgkmcnt(2)
	v_mfma_f32_32x32x16_f16 v[50:65], v[156:159], v[160:163], v[50:65]
	global_load_dwordx4 v[98:101], v134, s[14:15] offset:896
	s_waitcnt lgkmcnt(1)
	v_mfma_f32_32x32x16_f16 v[34:49], v[164:167], v[160:163], v[34:49]
	ds_read_b128 v[160:163], v144 offset:18464
	s_waitcnt vmcnt(8)
	ds_write_b128 v142, v[66:69]
	s_waitcnt lgkmcnt(2)
	v_mfma_f32_32x32x16_f16 v[18:33], v[156:159], v[168:171], v[18:33]
	ds_read_b128 v[156:159], v145 offset:55328
	global_load_dwordx4 v[102:105], v138, s[16:17] offset:896
	v_mfma_f32_32x32x16_f16 v[2:17], v[164:167], v[168:171], v[2:17]
	ds_read_b128 v[164:167], v145 offset:59936
	ds_read_b128 v[168:171], v144 offset:23072
	s_waitcnt vmcnt(8)
	ds_write_b128 v142, v[70:73] offset:36864
	s_waitcnt lgkmcnt(3)
	v_mfma_f32_32x32x16_f16 v[50:65], v[156:159], v[160:163], v[50:65]
	global_load_dwordx4 v[106:109], v135, s[14:15] offset:896
	s_waitcnt lgkmcnt(2)
	v_mfma_f32_32x32x16_f16 v[34:49], v[164:167], v[160:163], v[34:49]
	ds_read_b128 v[160:163], v144 offset:18496
	s_waitcnt vmcnt(8)
	ds_write_b128 v142, v[74:77] offset:4608
	s_waitcnt lgkmcnt(3)
	v_mfma_f32_32x32x16_f16 v[18:33], v[156:159], v[168:171], v[18:33]
	ds_read_b128 v[156:159], v145 offset:55360
	global_load_dwordx4 v[110:113], v139, s[16:17] offset:896
	v_mfma_f32_32x32x16_f16 v[2:17], v[164:167], v[168:171], v[2:17]
	ds_read_b128 v[164:167], v145 offset:59968
	ds_read_b128 v[168:171], v144 offset:23104
	s_waitcnt vmcnt(8)
	ds_write_b128 v142, v[78:81] offset:41472
	s_waitcnt lgkmcnt(3)
	v_mfma_f32_32x32x16_f16 v[50:65], v[156:159], v[160:163], v[50:65]
	global_load_dwordx4 v[114:117], v136, s[14:15] offset:896
	s_waitcnt lgkmcnt(2)
	v_mfma_f32_32x32x16_f16 v[34:49], v[164:167], v[160:163], v[34:49]
	ds_read_b128 v[160:163], v144 offset:18528
	s_waitcnt vmcnt(8)
	ds_write_b128 v142, v[82:85] offset:9216
	s_waitcnt lgkmcnt(3)
	v_mfma_f32_32x32x16_f16 v[18:33], v[156:159], v[168:171], v[18:33]
	ds_read_b128 v[156:159], v145 offset:55392
	global_load_dwordx4 v[118:121], v140, s[16:17] offset:896
	v_mfma_f32_32x32x16_f16 v[2:17], v[164:167], v[168:171], v[2:17]
	ds_read_b128 v[164:167], v145 offset:60000
	ds_read_b128 v[168:171], v144 offset:23136
	s_waitcnt vmcnt(8)
	ds_write_b128 v142, v[86:89] offset:46080
	s_waitcnt lgkmcnt(3)
	v_mfma_f32_32x32x16_f16 v[50:65], v[156:159], v[160:163], v[50:65]
	global_load_dwordx4 v[122:125], v137, s[14:15] offset:896
	s_waitcnt lgkmcnt(2)
	v_mfma_f32_32x32x16_f16 v[34:49], v[164:167], v[160:163], v[34:49]
	s_waitcnt vmcnt(8)
	ds_write_b128 v142, v[90:93] offset:13824
	s_waitcnt lgkmcnt(2)
	v_mfma_f32_32x32x16_f16 v[18:33], v[156:159], v[168:171], v[18:33]
	global_load_dwordx4 v[126:129], v141, s[16:17] offset:896
	v_mfma_f32_32x32x16_f16 v[2:17], v[164:167], v[168:171], v[2:17]
	s_waitcnt vmcnt(8)
	ds_write_b128 v142, v[94:97] offset:50688
	s_waitcnt lgkmcnt(0)
	s_barrier
	ds_read_b128 v[156:159], v145 offset:36864
	ds_read_b128 v[160:163], v144
	ds_read_b128 v[164:167], v145 offset:41472
	ds_read_b128 v[168:171], v144 offset:4608
	s_waitcnt lgkmcnt(2)
	v_mfma_f32_32x32x16_f16 v[50:65], v[156:159], v[160:163], v[50:65]
	global_load_dwordx4 v[66:69], v134, s[14:15] offset:1024
	s_waitcnt lgkmcnt(1)
	v_mfma_f32_32x32x16_f16 v[34:49], v[164:167], v[160:163], v[34:49]
	ds_read_b128 v[160:163], v144 offset:32
	s_waitcnt vmcnt(8)
	ds_write_b128 v142, v[98:101] offset:18432
	s_waitcnt lgkmcnt(2)
	v_mfma_f32_32x32x16_f16 v[18:33], v[156:159], v[168:171], v[18:33]
	ds_read_b128 v[156:159], v145 offset:36896
	global_load_dwordx4 v[70:73], v138, s[16:17] offset:1024
	v_mfma_f32_32x32x16_f16 v[2:17], v[164:167], v[168:171], v[2:17]
	ds_read_b128 v[164:167], v145 offset:41504
	ds_read_b128 v[168:171], v144 offset:4640
	s_waitcnt vmcnt(8)
	ds_write_b128 v142, v[102:105] offset:55296
	s_waitcnt lgkmcnt(3)
	v_mfma_f32_32x32x16_f16 v[50:65], v[156:159], v[160:163], v[50:65]
	global_load_dwordx4 v[74:77], v135, s[14:15] offset:1024
	s_waitcnt lgkmcnt(2)
	v_mfma_f32_32x32x16_f16 v[34:49], v[164:167], v[160:163], v[34:49]
	ds_read_b128 v[160:163], v144 offset:64
	s_waitcnt vmcnt(8)
	ds_write_b128 v142, v[106:109] offset:23040
	s_waitcnt lgkmcnt(3)
	v_mfma_f32_32x32x16_f16 v[18:33], v[156:159], v[168:171], v[18:33]
	ds_read_b128 v[156:159], v145 offset:36928
	global_load_dwordx4 v[78:81], v139, s[16:17] offset:1024
	v_mfma_f32_32x32x16_f16 v[2:17], v[164:167], v[168:171], v[2:17]
	ds_read_b128 v[164:167], v145 offset:41536
	ds_read_b128 v[168:171], v144 offset:4672
	s_waitcnt vmcnt(8)
	ds_write_b128 v142, v[110:113] offset:59904
	s_waitcnt lgkmcnt(3)
	v_mfma_f32_32x32x16_f16 v[50:65], v[156:159], v[160:163], v[50:65]
	global_load_dwordx4 v[82:85], v136, s[14:15] offset:1024
	s_waitcnt lgkmcnt(2)
	v_mfma_f32_32x32x16_f16 v[34:49], v[164:167], v[160:163], v[34:49]
	ds_read_b128 v[160:163], v144 offset:96
	s_waitcnt vmcnt(8)
	ds_write_b128 v142, v[114:117] offset:27648
	s_waitcnt lgkmcnt(3)
	v_mfma_f32_32x32x16_f16 v[18:33], v[156:159], v[168:171], v[18:33]
	ds_read_b128 v[156:159], v145 offset:36960
	global_load_dwordx4 v[86:89], v140, s[16:17] offset:1024
	v_mfma_f32_32x32x16_f16 v[2:17], v[164:167], v[168:171], v[2:17]
	ds_read_b128 v[164:167], v145 offset:41568
	ds_read_b128 v[168:171], v144 offset:4704
	s_waitcnt vmcnt(8)
	ds_write_b128 v142, v[118:121] offset:64512
	s_waitcnt lgkmcnt(3)
	v_mfma_f32_32x32x16_f16 v[50:65], v[156:159], v[160:163], v[50:65]
	global_load_dwordx4 v[90:93], v137, s[14:15] offset:1024
	s_waitcnt lgkmcnt(2)
	v_mfma_f32_32x32x16_f16 v[34:49], v[164:167], v[160:163], v[34:49]
	s_waitcnt vmcnt(8)
	ds_write_b128 v142, v[122:125] offset:32256
	s_waitcnt lgkmcnt(2)
	v_mfma_f32_32x32x16_f16 v[18:33], v[156:159], v[168:171], v[18:33]
	global_load_dwordx4 v[94:97], v141, s[16:17] offset:1024
	v_mfma_f32_32x32x16_f16 v[2:17], v[164:167], v[168:171], v[2:17]
	s_waitcnt vmcnt(8)
	ds_write_b128 v143, v[126:129] offset:64512
	s_waitcnt lgkmcnt(0)
	s_barrier
; #define GEMM_GLOAD(P, kt_) { GEMM_GL1(P, 0, kt_) GEMM_GL1(P, 1, kt_) GEMM_GL1(P, 2, kt_) GEMM_GL1(P, 3, kt_) }
; #define GEMM_LSTORE(P, buf_) { GEMM_LS1(P, 0, buf_) GEMM_LS1(P, 1, buf_) GEMM_LS1(P, 2, buf_) GEMM_LS1(P, 3, buf_) }
; template <bool DEEP>
; DI void gemm_mainloop_t(const u16* __restrict__ Ag, int lda, const u16* __restrict__ Bg, int ldb, int K, char* ldsraw,
;                         f32x16 (&acc)[2][2], int akstep) {
;     ...
;     for (int kt = 0; kt < nk; kt += 2) {
;       if (kt + 2 < nk) GEMM_GLOAD(x, kt + 2);
;       GEMM_COMPUTE(0);
;       GEMM_LSTORE(y, 1);
;       __syncthreads();
;       if (kt + 3 < nk) GEMM_GLOAD(y, kt + 3);
;       GEMM_COMPUTE(1);
;       if (kt + 2 < nk) GEMM_LSTORE(x, 0);
;       __syncthreads();
;     }
	ds_read_b128 v[156:159], v145 offset:55296
	ds_read_b128 v[160:163], v144 offset:18432
	ds_read_b128 v[164:167], v145 offset:59904
	ds_read_b128 v[168:171], v144 offset:23040
	s_waitcnt lgkmcnt(2)
	v_mfma_f32_32x32x16_f16 v[50:65], v[156:159], v[160:163], v[50:65]
	global_load_dwordx4 v[98:101], v134, s[14:15] offset:1152
	s_waitcnt lgkmcnt(1)
	v_mfma_f32_32x32x16_f16 v[34:49], v[164:167], v[160:163], v[34:49]
	ds_read_b128 v[160:163], v144 offset:18464
	s_waitcnt vmcnt(8)
	ds_write_b128 v142, v[66:69]
	s_waitcnt lgkmcnt(2)
	v_mfma_f32_32x32x16_f16 v[18:33], v[156:159], v[168:171], v[18:33]
	ds_read_b128 v[156:159], v145 offset:55328
	global_load_dwordx4 v[102:105], v138, s[16:17] offset:1152
	v_mfma_f32_32x32x16_f16 v[2:17], v[164:167], v[168:171], v[2:17]
	ds_read_b128 v[164:167], v145 offset:59936
	ds_read_b128 v[168:171], v144 offset:23072
	s_waitcnt vmcnt(8)
	ds_write_b128 v142, v[70:73] offset:36864
	s_waitcnt lgkmcnt(3)
	v_mfma_f32_32x32x16_f16 v[50:65], v[156:159], v[160:163], v[50:65]
	global_load_dwordx4 v[106:109], v135, s[14:15] offset:1152
	s_waitcnt lgkmcnt(2)
	v_mfma_f32_32x32x16_f16 v[34:49], v[164:167], v[160:163], v[34:49]
	ds_read_b128 v[160:163], v144 offset:18496
	s_waitcnt vmcnt(8)
	ds_write_b128 v142, v[74:77] offset:4608
	s_waitcnt lgkmcnt(3)
	v_mfma_f32_32x32x16_f16 v[18:33], v[156:159], v[168:171], v[18:33]
	ds_read_b128 v[156:159], v145 offset:55360
	global_load_dwordx4 v[110:113], v139, s[16:17] offset:1152
	v_mfma_f32_32x32x16_f16 v[2:17], v[164:167], v[168:171], v[2:17]
	ds_read_b128 v[164:167], v145 offset:59968
	ds_read_b128 v[168:171], v144 offset:23104
	s_waitcnt vmcnt(8)
	ds_write_b128 v142, v[78:81] offset:41472
	s_waitcnt lgkmcnt(3)
	v_mfma_f32_32x32x16_f16 v[50:65], v[156:159], v[160:163], v[50:65]
	global_load_dwordx4 v[114:117], v136, s[14:15] offset:1152
	s_waitcnt lgkmcnt(2)
	v_mfma_f32_32x32x16_f16 v[34:49], v[164:167], v[160:163], v[34:49]
	ds_read_b128 v[160:163], v144 offset:18528
	s_waitcnt vmcnt(8)
	ds_write_b128 v142, v[82:85] offset:9216
	s_waitcnt lgkmcnt(3)
	v_mfma_f32_32x32x16_f16 v[18:33], v[156:159], v[168:171], v[18:33]
	ds_read_b128 v[156:159], v145 offset:55392
	global_load_dwordx4 v[118:121], v140, s[16:17] offset:1152
	v_mfma_f32_32x32x16_f16 v[2:17], v[164:167], v[168:171], v[2:17]
	ds_read_b128 v[164:167], v145 offset:60000
	ds_read_b128 v[168:171], v144 offset:23136
	s_waitcnt vmcnt(8)
	ds_write_b128 v142, v[86:89] offset:46080
	s_waitcnt lgkmcnt(3)
	v_mfma_f32_32x32x16_f16 v[50:65], v[156:159], v[160:163], v[50:65]
	global_load_dwordx4 v[122:125], v137, s[14:15] offset:1152
	s_waitcnt lgkmcnt(2)
	v_mfma_f32_32x32x16_f16 v[34:49], v[164:167], v[160:163], v[34:49]
	s_waitcnt vmcnt(8)
	ds_write_b128 v142, v[90:93] offset:13824
	s_waitcnt lgkmcnt(2)
	v_mfma_f32_32x32x16_f16 v[18:33], v[156:159], v[168:171], v[18:33]
	global_load_dwordx4 v[126:129], v141, s[16:17] offset:1152
	v_mfma_f32_32x32x16_f16 v[2:17], v[164:167], v[168:171], v[2:17]
	s_waitcnt vmcnt(8)
	ds_write_b128 v142, v[94:97] offset:50688
	s_waitcnt lgkmcnt(0)
	s_barrier
	ds_read_b128 v[156:159], v145 offset:36864
	ds_read_b128 v[160:163], v144
	ds_read_b128 v[164:167], v145 offset:41472
	ds_read_b128 v[168:171], v144 offset:4608
	s_waitcnt lgkmcnt(2)
	v_mfma_f32_32x32x16_f16 v[50:65], v[156:159], v[160:163], v[50:65]
	global_load_dwordx4 v[66:69], v134, s[14:15] offset:1280
	s_waitcnt lgkmcnt(1)
	v_mfma_f32_32x32x16_f16 v[34:49], v[164:167], v[160:163], v[34:49]
	ds_read_b128 v[160:163], v144 offset:32
	s_waitcnt vmcnt(8)
	ds_write_b128 v142, v[98:101] offset:18432
	s_waitcnt lgkmcnt(2)
	v_mfma_f32_32x32x16_f16 v[18:33], v[156:159], v[168:171], v[18:33]
	ds_read_b128 v[156:159], v145 offset:36896
	global_load_dwordx4 v[70:73], v138, s[16:17] offset:1280
	v_mfma_f32_32x32x16_f16 v[2:17], v[164:167], v[168:171], v[2:17]
	ds_read_b128 v[164:167], v145 offset:41504
	ds_read_b128 v[168:171], v144 offset:4640
	s_waitcnt vmcnt(8)
	ds_write_b128 v142, v[102:105] offset:55296
	s_waitcnt lgkmcnt(3)
	v_mfma_f32_32x32x16_f16 v[50:65], v[156:159], v[160:163], v[50:65]
	global_load_dwordx4 v[74:77], v135, s[14:15] offset:1280
	s_waitcnt lgkmcnt(2)
	v_mfma_f32_32x32x16_f16 v[34:49], v[164:167], v[160:163], v[34:49]
	ds_read_b128 v[160:163], v144 offset:64
	s_waitcnt vmcnt(8)
	ds_write_b128 v142, v[106:109] offset:23040
	s_waitcnt lgkmcnt(3)
	v_mfma_f32_32x32x16_f16 v[18:33], v[156:159], v[168:171], v[18:33]
	ds_read_b128 v[156:159], v145 offset:36928
	global_load_dwordx4 v[78:81], v139, s[16:17] offset:1280
	v_mfma_f32_32x32x16_f16 v[2:17], v[164:167], v[168:171], v[2:17]
	ds_read_b128 v[164:167], v145 offset:41536
	ds_read_b128 v[168:171], v144 offset:4672
	s_waitcnt vmcnt(8)
	ds_write_b128 v142, v[110:113] offset:59904
	s_waitcnt lgkmcnt(3)
	v_mfma_f32_32x32x16_f16 v[50:65], v[156:159], v[160:163], v[50:65]
	global_load_dwordx4 v[82:85], v136, s[14:15] offset:1280
	s_waitcnt lgkmcnt(2)
	v_mfma_f32_32x32x16_f16 v[34:49], v[164:167], v[160:163], v[34:49]
	ds_read_b128 v[160:163], v144 offset:96
	s_waitcnt vmcnt(8)
	ds_write_b128 v142, v[114:117] offset:27648
	s_waitcnt lgkmcnt(3)
	v_mfma_f32_32x32x16_f16 v[18:33], v[156:159], v[168:171], v[18:33]
	ds_read_b128 v[156:159], v145 offset:36960
	global_load_dwordx4 v[86:89], v140, s[16:17] offset:1280
	v_mfma_f32_32x32x16_f16 v[2:17], v[164:167], v[168:171], v[2:17]
	ds_read_b128 v[164:167], v145 offset:41568
	ds_read_b128 v[168:171], v144 offset:4704
	s_waitcnt vmcnt(8)
	ds_write_b128 v142, v[118:121] offset:64512
	s_waitcnt lgkmcnt(3)
	v_mfma_f32_32x32x16_f16 v[50:65], v[156:159], v[160:163], v[50:65]
	global_load_dwordx4 v[90:93], v137, s[14:15] offset:1280
	s_waitcnt lgkmcnt(2)
	v_mfma_f32_32x32x16_f16 v[34:49], v[164:167], v[160:163], v[34:49]
	s_waitcnt vmcnt(8)
	ds_write_b128 v142, v[122:125] offset:32256
	s_waitcnt lgkmcnt(2)
	v_mfma_f32_32x32x16_f16 v[18:33], v[156:159], v[168:171], v[18:33]
	global_load_dwordx4 v[94:97], v141, s[16:17] offset:1280
	v_mfma_f32_32x32x16_f16 v[2:17], v[164:167], v[168:171], v[2:17]
	s_waitcnt vmcnt(8)
	ds_write_b128 v143, v[126:129] offset:64512
	s_waitcnt lgkmcnt(0)
	s_barrier
; #define GEMM_GLOAD(P, kt_) { GEMM_GL1(P, 0, kt_) GEMM_GL1(P, 1, kt_) GEMM_GL1(P, 2, kt_) GEMM_GL1(P, 3, kt_) }
; #define GEMM_LSTORE(P, buf_) { GEMM_LS1(P, 0, buf_) GEMM_LS1(P, 1, buf_) GEMM_LS1(P, 2, buf_) GEMM_LS1(P, 3, buf_) }
; template <bool DEEP>
; DI void gemm_mainloop_t(const u16* __restrict__ Ag, int lda, const u16* __restrict__ Bg, int ldb, int K, char* ldsraw,
;                         f32x16 (&acc)[2][2], int akstep) {
;     ...
;     for (int kt = 0; kt < nk; kt += 2) {
;       if (kt + 2 < nk) GEMM_GLOAD(x, kt + 2);
;       GEMM_COMPUTE(0);
;       GEMM_LSTORE(y, 1);
;       __syncthreads();
;       if (kt + 3 < nk) GEMM_GLOAD(y, kt + 3);
;       GEMM_COMPUTE(1);
;       if (kt + 2 < nk) GEMM_LSTORE(x, 0);
;       __syncthreads();
;     }
	ds_read_b128 v[156:159], v145 offset:55296
	ds_read_b128 v[160:163], v144 offset:18432
	ds_read_b128 v[164:167], v145 offset:59904
	ds_read_b128 v[168:171], v144 offset:23040
	s_waitcnt lgkmcnt(2)
	v_mfma_f32_32x32x16_f16 v[50:65], v[156:159], v[160:163], v[50:65]
	global_load_dwordx4 v[98:101], v134, s[14:15] offset:1408
	s_waitcnt lgkmcnt(1)
	v_mfma_f32_32x32x16_f16 v[34:49], v[164:167], v[160:163], v[34:49]
	ds_read_b128 v[160:163], v144 offset:18464
	s_waitcnt vmcnt(8)
	ds_write_b128 v142, v[66:69]
	s_waitcnt lgkmcnt(2)
	v_mfma_f32_32x32x16_f16 v[18:33], v[156:159], v[168:171], v[18:33]
	ds_read_b128 v[156:159], v145 offset:55328
	global_load_dwordx4 v[102:105], v138, s[16:17] offset:1408
	v_mfma_f32_32x32x16_f16 v[2:17], v[164:167], v[168:171], v[2:17]
	ds_read_b128 v[164:167], v145 offset:59936
	ds_read_b128 v[168:171], v144 offset:23072
	s_waitcnt vmcnt(8)
	ds_write_b128 v142, v[70:73] offset:36864
	s_waitcnt lgkmcnt(3)
	v_mfma_f32_32x32x16_f16 v[50:65], v[156:159], v[160:163], v[50:65]
	global_load_dwordx4 v[106:109], v135, s[14:15] offset:1408
	s_waitcnt lgkmcnt(2)
	v_mfma_f32_32x32x16_f16 v[34:49], v[164:167], v[160:163], v[34:49]
	ds_read_b128 v[160:163], v144 offset:18496
	s_waitcnt vmcnt(8)
	ds_write_b128 v142, v[74:77] offset:4608
	s_waitcnt lgkmcnt(3)
	v_mfma_f32_32x32x16_f16 v[18:33], v[156:159], v[168:171], v[18:33]
	ds_read_b128 v[156:159], v145 offset:55360
	global_load_dwordx4 v[110:113], v139, s[16:17] offset:1408
	v_mfma_f32_32x32x16_f16 v[2:17], v[164:167], v[168:171], v[2:17]
	ds_read_b128 v[164:167], v145 offset:59968
	ds_read_b128 v[168:171], v144 offset:23104
	s_waitcnt vmcnt(8)
	ds_write_b128 v142, v[78:81] offset:41472
	s_waitcnt lgkmcnt(3)
	v_mfma_f32_32x32x16_f16 v[50:65], v[156:159], v[160:163], v[50:65]
	global_load_dwordx4 v[114:117], v136, s[14:15] offset:1408
	s_waitcnt lgkmcnt(2)
	v_mfma_f32_32x32x16_f16 v[34:49], v[164:167], v[160:163], v[34:49]
	ds_read_b128 v[160:163], v144 offset:18528
	s_waitcnt vmcnt(8)
	ds_write_b128 v142, v[82:85] offset:9216
	s_waitcnt lgkmcnt(3)
	v_mfma_f32_32x32x16_f16 v[18:33], v[156:159], v[168:171], v[18:33]
	ds_read_b128 v[156:159], v145 offset:55392
	global_load_dwordx4 v[118:121], v140, s[16:17] offset:1408
	v_mfma_f32_32x32x16_f16 v[2:17], v[164:167], v[168:171], v[2:17]
	ds_read_b128 v[164:167], v145 offset:60000
	ds_read_b128 v[168:171], v144 offset:23136
	s_waitcnt vmcnt(8)
	ds_write_b128 v142, v[86:89] offset:46080
	s_waitcnt lgkmcnt(3)
	v_mfma_f32_32x32x16_f16 v[50:65], v[156:159], v[160:163], v[50:65]
	global_load_dwordx4 v[122:125], v137, s[14:15] offset:1408
	s_waitcnt lgkmcnt(2)
	v_mfma_f32_32x32x16_f16 v[34:49], v[164:167], v[160:163], v[34:49]
	s_waitcnt vmcnt(8)
	ds_write_b128 v142, v[90:93] offset:13824
	s_waitcnt lgkmcnt(2)
	v_mfma_f32_32x32x16_f16 v[18:33], v[156:159], v[168:171], v[18:33]
	global_load_dwordx4 v[126:129], v141, s[16:17] offset:1408
	v_mfma_f32_32x32x16_f16 v[2:17], v[164:167], v[168:171], v[2:17]
	s_waitcnt vmcnt(8)
	ds_write_b128 v142, v[94:97] offset:50688
	s_waitcnt lgkmcnt(0)
	s_barrier
	ds_read_b128 v[156:159], v145 offset:36864
	ds_read_b128 v[160:163], v144
	ds_read_b128 v[164:167], v145 offset:41472
	ds_read_b128 v[168:171], v144 offset:4608
	s_waitcnt lgkmcnt(2)
	v_mfma_f32_32x32x16_f16 v[50:65], v[156:159], v[160:163], v[50:65]
	global_load_dwordx4 v[66:69], v134, s[14:15] offset:1536
	s_waitcnt lgkmcnt(1)
	v_mfma_f32_32x32x16_f16 v[34:49], v[164:167], v[160:163], v[34:49]
	ds_read_b128 v[160:163], v144 offset:32
	s_waitcnt vmcnt(8)
	ds_write_b128 v142, v[98:101] offset:18432
	s_waitcnt lgkmcnt(2)
	v_mfma_f32_32x32x16_f16 v[18:33], v[156:159], v[168:171], v[18:33]
	ds_read_b128 v[156:159], v145 offset:36896
	global_load_dwordx4 v[70:73], v138, s[16:17] offset:1536
	v_mfma_f32_32x32x16_f16 v[2:17], v[164:167], v[168:171], v[2:17]
	ds_read_b128 v[164:167], v145 offset:41504
	ds_read_b128 v[168:171], v144 offset:4640
	s_waitcnt vmcnt(8)
	ds_write_b128 v142, v[102:105] offset:55296
	s_waitcnt lgkmcnt(3)
	v_mfma_f32_32x32x16_f16 v[50:65], v[156:159], v[160:163], v[50:65]
	global_load_dwordx4 v[74:77], v135, s[14:15] offset:1536
	s_waitcnt lgkmcnt(2)
	v_mfma_f32_32x32x16_f16 v[34:49], v[164:167], v[160:163], v[34:49]
	ds_read_b128 v[160:163], v144 offset:64
	s_waitcnt vmcnt(8)
	ds_write_b128 v142, v[106:109] offset:23040
	s_waitcnt lgkmcnt(3)
	v_mfma_f32_32x32x16_f16 v[18:33], v[156:159], v[168:171], v[18:33]
	ds_read_b128 v[156:159], v145 offset:36928
	global_load_dwordx4 v[78:81], v139, s[16:17] offset:1536
	v_mfma_f32_32x32x16_f16 v[2:17], v[164:167], v[168:171], v[2:17]
	ds_read_b128 v[164:167], v145 offset:41536
	ds_read_b128 v[168:171], v144 offset:4672
	s_waitcnt vmcnt(8)
	ds_write_b128 v142, v[110:113] offset:59904
	s_waitcnt lgkmcnt(3)
	v_mfma_f32_32x32x16_f16 v[50:65], v[156:159], v[160:163], v[50:65]
	global_load_dwordx4 v[82:85], v136, s[14:15] offset:1536
	s_waitcnt lgkmcnt(2)
	v_mfma_f32_32x32x16_f16 v[34:49], v[164:167], v[160:163], v[34:49]
	ds_read_b128 v[160:163], v144 offset:96
	s_waitcnt vmcnt(8)
	ds_write_b128 v142, v[114:117] offset:27648
	s_waitcnt lgkmcnt(3)
	v_mfma_f32_32x32x16_f16 v[18:33], v[156:159], v[168:171], v[18:33]
	ds_read_b128 v[156:159], v145 offset:36960
	global_load_dwordx4 v[86:89], v140, s[16:17] offset:1536
	v_mfma_f32_32x32x16_f16 v[2:17], v[164:167], v[168:171], v[2:17]
	ds_read_b128 v[164:167], v145 offset:41568
	ds_read_b128 v[168:171], v144 offset:4704
	s_waitcnt vmcnt(8)
	ds_write_b128 v142, v[118:121] offset:64512
	s_waitcnt lgkmcnt(3)
	v_mfma_f32_32x32x16_f16 v[50:65], v[156:159], v[160:163], v[50:65]
	global_load_dwordx4 v[90:93], v137, s[14:15] offset:1536
	s_waitcnt lgkmcnt(2)
	v_mfma_f32_32x32x16_f16 v[34:49], v[164:167], v[160:163], v[34:49]
	s_waitcnt vmcnt(8)
	ds_write_b128 v142, v[122:125] offset:32256
	s_waitcnt lgkmcnt(2)
	v_mfma_f32_32x32x16_f16 v[18:33], v[156:159], v[168:171], v[18:33]
	global_load_dwordx4 v[94:97], v141, s[16:17] offset:1536
	v_mfma_f32_32x32x16_f16 v[2:17], v[164:167], v[168:171], v[2:17]
	s_waitcnt vmcnt(8)
	ds_write_b128 v143, v[126:129] offset:64512
	s_waitcnt lgkmcnt(0)
	s_barrier
; #define GEMM_GLOAD(P, kt_) { GEMM_GL1(P, 0, kt_) GEMM_GL1(P, 1, kt_) GEMM_GL1(P, 2, kt_) GEMM_GL1(P, 3, kt_) }
; #define GEMM_LSTORE(P, buf_) { GEMM_LS1(P, 0, buf_) GEMM_LS1(P, 1, buf_) GEMM_LS1(P, 2, buf_) GEMM_LS1(P, 3, buf_) }
; template <bool DEEP>
; DI void gemm_mainloop_t(const u16* __restrict__ Ag, int lda, const u16* __restrict__ Bg, int ldb, int K, char* ldsraw,
;                         f32x16 (&acc)[2][2], int akstep) {
;     ...
;     for (int kt = 0; kt < nk; kt += 2) {
;       if (kt + 2 < nk) GEMM_GLOAD(x, kt + 2);
;       GEMM_COMPUTE(0);
;       GEMM_LSTORE(y, 1);
;       __syncthreads();
;       if (kt + 3 < nk) GEMM_GLOAD(y, kt + 3);
;       GEMM_COMPUTE(1);
;       if (kt + 2 < nk) GEMM_LSTORE(x, 0);
;       __syncthreads();
;     }
	ds_read_b128 v[156:159], v145 offset:55296
	ds_read_b128 v[160:163], v144 offset:18432
	ds_read_b128 v[164:167], v145 offset:59904
	ds_read_b128 v[168:171], v144 offset:23040
	s_waitcnt lgkmcnt(2)
	v_mfma_f32_32x32x16_f16 v[50:65], v[156:159], v[160:163], v[50:65]
	global_load_dwordx4 v[98:101], v134, s[14:15] offset:1664
	s_waitcnt lgkmcnt(1)
	v_mfma_f32_32x32x16_f16 v[34:49], v[164:167], v[160:163], v[34:49]
	ds_read_b128 v[160:163], v144 offset:18464
	s_waitcnt vmcnt(8)
	ds_write_b128 v142, v[66:69]
	s_waitcnt lgkmcnt(2)
	v_mfma_f32_32x32x16_f16 v[18:33], v[156:159], v[168:171], v[18:33]
	ds_read_b128 v[156:159], v145 offset:55328
	global_load_dwordx4 v[102:105], v138, s[16:17] offset:1664
	v_mfma_f32_32x32x16_f16 v[2:17], v[164:167], v[168:171], v[2:17]
	ds_read_b128 v[164:167], v145 offset:59936
	ds_read_b128 v[168:171], v144 offset:23072
	s_waitcnt vmcnt(8)
	ds_write_b128 v142, v[70:73] offset:36864
	s_waitcnt lgkmcnt(3)
	v_mfma_f32_32x32x16_f16 v[50:65], v[156:159], v[160:163], v[50:65]
	global_load_dwordx4 v[106:109], v135, s[14:15] offset:1664
	s_waitcnt lgkmcnt(2)
	v_mfma_f32_32x32x16_f16 v[34:49], v[164:167], v[160:163], v[34:49]
	ds_read_b128 v[160:163], v144 offset:18496
	s_waitcnt vmcnt(8)
	ds_write_b128 v142, v[74:77] offset:4608
	s_waitcnt lgkmcnt(3)
	v_mfma_f32_32x32x16_f16 v[18:33], v[156:159], v[168:171], v[18:33]
	ds_read_b128 v[156:159], v145 offset:55360
	global_load_dwordx4 v[110:113], v139, s[16:17] offset:1664
	v_mfma_f32_32x32x16_f16 v[2:17], v[164:167], v[168:171], v[2:17]
	ds_read_b128 v[164:167], v145 offset:59968
	ds_read_b128 v[168:171], v144 offset:23104
	s_waitcnt vmcnt(8)
	ds_write_b128 v142, v[78:81] offset:41472
	s_waitcnt lgkmcnt(3)
	v_mfma_f32_32x32x16_f16 v[50:65], v[156:159], v[160:163], v[50:65]
	global_load_dwordx4 v[114:117], v136, s[14:15] offset:1664
	s_waitcnt lgkmcnt(2)
	v_mfma_f32_32x32x16_f16 v[34:49], v[164:167], v[160:163], v[34:49]
	ds_read_b128 v[160:163], v144 offset:18528
	s_waitcnt vmcnt(8)
	ds_write_b128 v142, v[82:85] offset:9216
	s_waitcnt lgkmcnt(3)
	v_mfma_f32_32x32x16_f16 v[18:33], v[156:159], v[168:171], v[18:33]
	ds_read_b128 v[156:159], v145 offset:55392
	global_load_dwordx4 v[118:121], v140, s[16:17] offset:1664
	v_mfma_f32_32x32x16_f16 v[2:17], v[164:167], v[168:171], v[2:17]
	ds_read_b128 v[164:167], v145 offset:60000
	ds_read_b128 v[168:171], v144 offset:23136
	s_waitcnt vmcnt(8)
	ds_write_b128 v142, v[86:89] offset:46080
	s_waitcnt lgkmcnt(3)
	v_mfma_f32_32x32x16_f16 v[50:65], v[156:159], v[160:163], v[50:65]
	global_load_dwordx4 v[122:125], v137, s[14:15] offset:1664
	s_waitcnt lgkmcnt(2)
	v_mfma_f32_32x32x16_f16 v[34:49], v[164:167], v[160:163], v[34:49]
	s_waitcnt vmcnt(8)
	ds_write_b128 v142, v[90:93] offset:13824
	s_waitcnt lgkmcnt(2)
	v_mfma_f32_32x32x16_f16 v[18:33], v[156:159], v[168:171], v[18:33]
	global_load_dwordx4 v[126:129], v141, s[16:17] offset:1664
	v_mfma_f32_32x32x16_f16 v[2:17], v[164:167], v[168:171], v[2:17]
	s_waitcnt vmcnt(8)
	ds_write_b128 v142, v[94:97] offset:50688
	s_waitcnt lgkmcnt(0)
	s_barrier
	ds_read_b128 v[156:159], v145 offset:36864
	ds_read_b128 v[160:163], v144
	ds_read_b128 v[164:167], v145 offset:41472
	ds_read_b128 v[168:171], v144 offset:4608
	s_waitcnt lgkmcnt(2)
	v_mfma_f32_32x32x16_f16 v[50:65], v[156:159], v[160:163], v[50:65]
	global_load_dwordx4 v[66:69], v134, s[14:15] offset:1792
	s_waitcnt lgkmcnt(1)
	v_mfma_f32_32x32x16_f16 v[34:49], v[164:167], v[160:163], v[34:49]
	ds_read_b128 v[160:163], v144 offset:32
	s_waitcnt vmcnt(8)
	ds_write_b128 v142, v[98:101] offset:18432
	s_waitcnt lgkmcnt(2)
	v_mfma_f32_32x32x16_f16 v[18:33], v[156:159], v[168:171], v[18:33]
	ds_read_b128 v[156:159], v145 offset:36896
	global_load_dwordx4 v[70:73], v138, s[16:17] offset:1792
	v_mfma_f32_32x32x16_f16 v[2:17], v[164:167], v[168:171], v[2:17]
	ds_read_b128 v[164:167], v145 offset:41504
	ds_read_b128 v[168:171], v144 offset:4640
	s_waitcnt vmcnt(8)
	ds_write_b128 v142, v[102:105] offset:55296
	s_waitcnt lgkmcnt(3)
	v_mfma_f32_32x32x16_f16 v[50:65], v[156:159], v[160:163], v[50:65]
	global_load_dwordx4 v[74:77], v135, s[14:15] offset:1792
	s_waitcnt lgkmcnt(2)
	v_mfma_f32_32x32x16_f16 v[34:49], v[164:167], v[160:163], v[34:49]
	ds_read_b128 v[160:163], v144 offset:64
	s_waitcnt vmcnt(8)
	ds_write_b128 v142, v[106:109] offset:23040
	s_waitcnt lgkmcnt(3)
	v_mfma_f32_32x32x16_f16 v[18:33], v[156:159], v[168:171], v[18:33]
	ds_read_b128 v[156:159], v145 offset:36928
	global_load_dwordx4 v[78:81], v139, s[16:17] offset:1792
	v_mfma_f32_32x32x16_f16 v[2:17], v[164:167], v[168:171], v[2:17]
	ds_read_b128 v[164:167], v145 offset:41536
	ds_read_b128 v[168:171], v144 offset:4672
	s_waitcnt vmcnt(8)
	ds_write_b128 v142, v[110:113] offset:59904
	s_waitcnt lgkmcnt(3)
	v_mfma_f32_32x32x16_f16 v[50:65], v[156:159], v[160:163], v[50:65]
	global_load_dwordx4 v[82:85], v136, s[14:15] offset:1792
	s_waitcnt lgkmcnt(2)
	v_mfma_f32_32x32x16_f16 v[34:49], v[164:167], v[160:163], v[34:49]
	ds_read_b128 v[160:163], v144 offset:96
	s_waitcnt vmcnt(8)
	ds_write_b128 v142, v[114:117] offset:27648
	s_waitcnt lgkmcnt(3)
	v_mfma_f32_32x32x16_f16 v[18:33], v[156:159], v[168:171], v[18:33]
	ds_read_b128 v[156:159], v145 offset:36960
	global_load_dwordx4 v[86:89], v140, s[16:17] offset:1792
	v_mfma_f32_32x32x16_f16 v[2:17], v[164:167], v[168:171], v[2:17]
	ds_read_b128 v[164:167], v145 offset:41568
	ds_read_b128 v[168:171], v144 offset:4704
	s_waitcnt vmcnt(8)
	ds_write_b128 v142, v[118:121] offset:64512
	s_waitcnt lgkmcnt(3)
	v_mfma_f32_32x32x16_f16 v[50:65], v[156:159], v[160:163], v[50:65]
	global_load_dwordx4 v[90:93], v137, s[14:15] offset:1792
	s_waitcnt lgkmcnt(2)
	v_mfma_f32_32x32x16_f16 v[34:49], v[164:167], v[160:163], v[34:49]
	s_waitcnt vmcnt(8)
	ds_write_b128 v142, v[122:125] offset:32256
	s_waitcnt lgkmcnt(2)
	v_mfma_f32_32x32x16_f16 v[18:33], v[156:159], v[168:171], v[18:33]
	global_load_dwordx4 v[94:97], v141, s[16:17] offset:1792
	v_mfma_f32_32x32x16_f16 v[2:17], v[164:167], v[168:171], v[2:17]
	s_waitcnt vmcnt(8)
	ds_write_b128 v143, v[126:129] offset:64512
	s_waitcnt lgkmcnt(0)
	s_barrier
; #define GEMM_GLOAD(P, kt_) { GEMM_GL1(P, 0, kt_) GEMM_GL1(P, 1, kt_) GEMM_GL1(P, 2, kt_) GEMM_GL1(P, 3, kt_) }
; #define GEMM_LSTORE(P, buf_) { GEMM_LS1(P, 0, buf_) GEMM_LS1(P, 1, buf_) GEMM_LS1(P, 2, buf_) GEMM_LS1(P, 3, buf_) }
; template <bool DEEP>
; DI void gemm_mainloop_t(const u16* __restrict__ Ag, int lda, const u16* __restrict__ Bg, int ldb, int K, char* ldsraw,
;                         f32x16 (&acc)[2][2], int akstep) {
;     ...
;     for (int kt = 0; kt < nk; kt += 2) {
;       if (kt + 2 < nk) GEMM_GLOAD(x, kt + 2);
;       GEMM_COMPUTE(0);
;       GEMM_LSTORE(y, 1);
;       __syncthreads();
;       if (kt + 3 < nk) GEMM_GLOAD(y, kt + 3);
;       GEMM_COMPUTE(1);
;       if (kt + 2 < nk) GEMM_LSTORE(x, 0);
;       __syncthreads();
;     }
	ds_read_b128 v[156:159], v145 offset:55296
	ds_read_b128 v[160:163], v144 offset:18432
	ds_read_b128 v[164:167], v145 offset:59904
	ds_read_b128 v[168:171], v144 offset:23040
	s_waitcnt lgkmcnt(2)
	v_mfma_f32_32x32x16_f16 v[50:65], v[156:159], v[160:163], v[50:65]
	global_load_dwordx4 v[98:101], v134, s[14:15] offset:1920
	s_waitcnt lgkmcnt(1)
	v_mfma_f32_32x32x16_f16 v[34:49], v[164:167], v[160:163], v[34:49]
	ds_read_b128 v[160:163], v144 offset:18464
	s_waitcnt vmcnt(8)
	ds_write_b128 v142, v[66:69]
	s_waitcnt lgkmcnt(2)
	v_mfma_f32_32x32x16_f16 v[18:33], v[156:159], v[168:171], v[18:33]
	ds_read_b128 v[156:159], v145 offset:55328
	global_load_dwordx4 v[102:105], v138, s[16:17] offset:1920
	v_mfma_f32_32x32x16_f16 v[2:17], v[164:167], v[168:171], v[2:17]
	ds_read_b128 v[164:167], v145 offset:59936
	ds_read_b128 v[168:171], v144 offset:23072
	s_waitcnt vmcnt(8)
	ds_write_b128 v142, v[70:73] offset:36864
	s_waitcnt lgkmcnt(3)
	v_mfma_f32_32x32x16_f16 v[50:65], v[156:159], v[160:163], v[50:65]
	global_load_dwordx4 v[106:109], v135, s[14:15] offset:1920
	s_waitcnt lgkmcnt(2)
	v_mfma_f32_32x32x16_f16 v[34:49], v[164:167], v[160:163], v[34:49]
	ds_read_b128 v[160:163], v144 offset:18496
	s_waitcnt vmcnt(8)
	ds_write_b128 v142, v[74:77] offset:4608
	s_waitcnt lgkmcnt(3)
	v_mfma_f32_32x32x16_f16 v[18:33], v[156:159], v[168:171], v[18:33]
	ds_read_b128 v[156:159], v145 offset:55360
	global_load_dwordx4 v[110:113], v139, s[16:17] offset:1920
	v_mfma_f32_32x32x16_f16 v[2:17], v[164:167], v[168:171], v[2:17]
	ds_read_b128 v[164:167], v145 offset:59968
	ds_read_b128 v[168:171], v144 offset:23104
	s_waitcnt vmcnt(8)
	ds_write_b128 v142, v[78:81] offset:41472
	s_waitcnt lgkmcnt(3)
	v_mfma_f32_32x32x16_f16 v[50:65], v[156:159], v[160:163], v[50:65]
	global_load_dwordx4 v[114:117], v136, s[14:15] offset:1920
	s_waitcnt lgkmcnt(2)
	v_mfma_f32_32x32x16_f16 v[34:49], v[164:167], v[160:163], v[34:49]
	ds_read_b128 v[160:163], v144 offset:18528
	s_waitcnt vmcnt(8)
	ds_write_b128 v142, v[82:85] offset:9216
	s_waitcnt lgkmcnt(3)
	v_mfma_f32_32x32x16_f16 v[18:33], v[156:159], v[168:171], v[18:33]
	ds_read_b128 v[156:159], v145 offset:55392
	global_load_dwordx4 v[118:121], v140, s[16:17] offset:1920
	v_mfma_f32_32x32x16_f16 v[2:17], v[164:167], v[168:171], v[2:17]
	ds_read_b128 v[164:167], v145 offset:60000
	ds_read_b128 v[168:171], v144 offset:23136
	s_waitcnt vmcnt(8)
	ds_write_b128 v142, v[86:89] offset:46080
	s_waitcnt lgkmcnt(3)
	v_mfma_f32_32x32x16_f16 v[50:65], v[156:159], v[160:163], v[50:65]
	global_load_dwordx4 v[122:125], v137, s[14:15] offset:1920
	s_waitcnt lgkmcnt(2)
	v_mfma_f32_32x32x16_f16 v[34:49], v[164:167], v[160:163], v[34:49]
	s_waitcnt vmcnt(8)
	ds_write_b128 v142, v[90:93] offset:13824
	s_waitcnt lgkmcnt(2)
	v_mfma_f32_32x32x16_f16 v[18:33], v[156:159], v[168:171], v[18:33]
	global_load_dwordx4 v[126:129], v141, s[16:17] offset:1920
	v_mfma_f32_32x32x16_f16 v[2:17], v[164:167], v[168:171], v[2:17]
	s_waitcnt vmcnt(8)
	ds_write_b128 v142, v[94:97] offset:50688
	s_waitcnt lgkmcnt(0)
	s_barrier
; #define GEMM_GLOAD(P, kt_) { GEMM_GL1(P, 0, kt_) GEMM_GL1(P, 1, kt_) GEMM_GL1(P, 2, kt_) GEMM_GL1(P, 3, kt_) }
; #define GEMM_LSTORE(P, buf_) { GEMM_LS1(P, 0, buf_) GEMM_LS1(P, 1, buf_) GEMM_LS1(P, 2, buf_) GEMM_LS1(P, 3, buf_) }
; template <bool DEEP>
; DI void gemm_mainloop_t(const u16* __restrict__ Ag, int lda, const u16* __restrict__ Bg, int ldb, int K, char* ldsraw,
;                         f32x16 (&acc)[2][2], int akstep) {
;     ...
;     for (int kt = 0; kt < nk; kt += 2) {
;       if (kt + 2 < nk) GEMM_GLOAD(x, kt + 2);
;       GEMM_COMPUTE(0);
;       GEMM_LSTORE(y, 1);
;       __syncthreads();
;       if (kt + 3 < nk) GEMM_GLOAD(y, kt + 3);
;       GEMM_COMPUTE(1);
;       if (kt + 2 < nk) GEMM_LSTORE(x, 0);
;       __syncthreads();
;     }
; DI void phase1(const Params& p, int l, char* lds) {
;     ...
;       const int col0 = nt * 128 + wn * 64;
;       const float* gain = nullptr;
;       float sc = 1.f;
;       if (col0 < 512) { gain = p.qn_a + l * 64; sc = QSCALE; }
;       else if (col0 < 1024) { gain = p.kn_a + l * 64; }
;       else if (col0 >= QC && col0 < QC + 512) { gain = p.qn_c + l * 64; sc = QSCALE; }
;       else if ((col0 >= KSC && col0 < KSC + 128) || (col0 >= KWC && col0 < KWC + 128)) { gain = p.kn_c + l * 64; }
;       if (gain != nullptr) {
	ds_read_b128 v[156:159], v145 offset:36864
	ds_read_b128 v[160:163], v144
	ds_read_b128 v[164:167], v145 offset:41472
	ds_read_b128 v[168:171], v144 offset:4608
	s_waitcnt lgkmcnt(2)
	v_mfma_f32_32x32x16_f16 v[50:65], v[156:159], v[160:163], v[50:65]
	s_waitcnt lgkmcnt(1)
	v_mfma_f32_32x32x16_f16 v[34:49], v[164:167], v[160:163], v[34:49]
	ds_read_b128 v[160:163], v144 offset:32
	s_waitcnt vmcnt(7)
	ds_write_b128 v142, v[98:101] offset:18432
	s_waitcnt lgkmcnt(2)
	v_mfma_f32_32x32x16_f16 v[18:33], v[156:159], v[168:171], v[18:33]
	ds_read_b128 v[156:159], v145 offset:36896
	v_mfma_f32_32x32x16_f16 v[2:17], v[164:167], v[168:171], v[2:17]
	ds_read_b128 v[164:167], v145 offset:41504
	ds_read_b128 v[168:171], v144 offset:4640
	s_waitcnt vmcnt(6)
	ds_write_b128 v142, v[102:105] offset:55296
	s_waitcnt lgkmcnt(3)
	v_mfma_f32_32x32x16_f16 v[50:65], v[156:159], v[160:163], v[50:65]
	s_waitcnt lgkmcnt(2)
	v_mfma_f32_32x32x16_f16 v[34:49], v[164:167], v[160:163], v[34:49]
	ds_read_b128 v[160:163], v144 offset:64
	s_waitcnt vmcnt(5)
	ds_write_b128 v142, v[106:109] offset:23040
	s_waitcnt lgkmcnt(3)
	v_mfma_f32_32x32x16_f16 v[18:33], v[156:159], v[168:171], v[18:33]
	ds_read_b128 v[156:159], v145 offset:36928
	v_mfma_f32_32x32x16_f16 v[2:17], v[164:167], v[168:171], v[2:17]
	ds_read_b128 v[164:167], v145 offset:41536
	ds_read_b128 v[168:171], v144 offset:4672
	s_waitcnt vmcnt(4)
	ds_write_b128 v142, v[110:113] offset:59904
	s_waitcnt lgkmcnt(3)
	v_mfma_f32_32x32x16_f16 v[50:65], v[156:159], v[160:163], v[50:65]
	s_waitcnt lgkmcnt(2)
	v_mfma_f32_32x32x16_f16 v[34:49], v[164:167], v[160:163], v[34:49]
	ds_read_b128 v[160:163], v144 offset:96
	s_waitcnt vmcnt(3)
	ds_write_b128 v142, v[114:117] offset:27648
	s_waitcnt lgkmcnt(3)
	v_mfma_f32_32x32x16_f16 v[18:33], v[156:159], v[168:171], v[18:33]
	ds_read_b128 v[156:159], v145 offset:36960
	v_mfma_f32_32x32x16_f16 v[2:17], v[164:167], v[168:171], v[2:17]
	ds_read_b128 v[164:167], v145 offset:41568
	ds_read_b128 v[168:171], v144 offset:4704
	s_waitcnt vmcnt(2)
	ds_write_b128 v142, v[118:121] offset:64512
	s_waitcnt lgkmcnt(3)
	v_mfma_f32_32x32x16_f16 v[50:65], v[156:159], v[160:163], v[50:65]
	s_waitcnt lgkmcnt(2)
	v_mfma_f32_32x32x16_f16 v[34:49], v[164:167], v[160:163], v[34:49]
	s_waitcnt vmcnt(1)
	ds_write_b128 v142, v[122:125] offset:32256
	s_waitcnt lgkmcnt(2)
	v_mfma_f32_32x32x16_f16 v[18:33], v[156:159], v[168:171], v[18:33]
	v_mfma_f32_32x32x16_f16 v[2:17], v[164:167], v[168:171], v[2:17]
	s_waitcnt vmcnt(0)
	ds_write_b128 v143, v[126:129] offset:64512
	s_waitcnt lgkmcnt(0)
	s_barrier
	ds_read_b128 v[156:159], v145 offset:55296
	ds_read_b128 v[160:163], v144 offset:18432
	ds_read_b128 v[164:167], v145 offset:59904
	ds_read_b128 v[168:171], v144 offset:23040
	s_waitcnt lgkmcnt(2)
	v_mfma_f32_32x32x16_f16 v[50:65], v[156:159], v[160:163], v[50:65]
	s_waitcnt lgkmcnt(1)
	v_mfma_f32_32x32x16_f16 v[34:49], v[164:167], v[160:163], v[34:49]
	ds_read_b128 v[160:163], v144 offset:18464
	s_waitcnt lgkmcnt(1)
	v_mfma_f32_32x32x16_f16 v[18:33], v[156:159], v[168:171], v[18:33]
	ds_read_b128 v[156:159], v145 offset:55328
	v_mfma_f32_32x32x16_f16 v[2:17], v[164:167], v[168:171], v[2:17]
	ds_read_b128 v[164:167], v145 offset:59936
	ds_read_b128 v[168:171], v144 offset:23072
	s_waitcnt lgkmcnt(2)
	v_mfma_f32_32x32x16_f16 v[50:65], v[156:159], v[160:163], v[50:65]
	s_waitcnt lgkmcnt(1)
	v_mfma_f32_32x32x16_f16 v[34:49], v[164:167], v[160:163], v[34:49]
	ds_read_b128 v[160:163], v144 offset:18496
	s_waitcnt lgkmcnt(1)
	v_mfma_f32_32x32x16_f16 v[18:33], v[156:159], v[168:171], v[18:33]
	ds_read_b128 v[156:159], v145 offset:55360
	v_mfma_f32_32x32x16_f16 v[2:17], v[164:167], v[168:171], v[2:17]
	ds_read_b128 v[164:167], v145 offset:59968
	ds_read_b128 v[168:171], v144 offset:23104
	s_waitcnt lgkmcnt(2)
	v_mfma_f32_32x32x16_f16 v[50:65], v[156:159], v[160:163], v[50:65]
	s_waitcnt lgkmcnt(1)
	v_mfma_f32_32x32x16_f16 v[34:49], v[164:167], v[160:163], v[34:49]
	ds_read_b128 v[160:163], v144 offset:18528
	s_waitcnt lgkmcnt(1)
	v_mfma_f32_32x32x16_f16 v[18:33], v[156:159], v[168:171], v[18:33]
	ds_read_b128 v[156:159], v145 offset:55392
	v_mfma_f32_32x32x16_f16 v[2:17], v[164:167], v[168:171], v[2:17]
	ds_read_b128 v[164:167], v145 offset:60000
	ds_read_b128 v[168:171], v144 offset:23136
	s_waitcnt lgkmcnt(2)
	v_mfma_f32_32x32x16_f16 v[50:65], v[156:159], v[160:163], v[50:65]
	s_waitcnt lgkmcnt(1)
	v_mfma_f32_32x32x16_f16 v[34:49], v[164:167], v[160:163], v[34:49]
	s_waitcnt lgkmcnt(0)
	v_mfma_f32_32x32x16_f16 v[18:33], v[156:159], v[168:171], v[18:33]
	v_mfma_f32_32x32x16_f16 v[2:17], v[164:167], v[168:171], v[2:17]
	s_nop 1
	s_lshl_b32 s16, s0, 7
	v_or_b32_e32 v83, s16, v131
	s_movk_i32 s1, 0x1ff
	v_cmp_lt_i32_e32 vcc, s1, v83
	v_mov_b32_e32 v68, 0x3e38aa3b
	v_mov_b64_e32 v[66:67], s[10:11]
	s_barrier
	s_and_saveexec_b64 s[14:15], vcc
	s_cbranch_execz .LBB0_230
	s_mov_b32 s1, 1.0
	s_cmpk_lt_u32 s16, 0x400
	s_mov_b64 s[16:17], s[8:9]
	s_cbranch_scc1 .LBB0_229
	s_and_b32 s16, s18, 0x3fffff80
	s_mov_b32 s1, 0x3e38aa3b
	s_cmpk_eq_i32 s16, 0x300
	s_mov_b64 s[16:17], s[6:7]
	s_cbranch_scc1 .LBB0_229
	s_cmp_lt_i32 s0, 32
	s_cbranch_scc1 .LBB0_224
	s_cmp_eq_u32 s0, 32
	s_cselect_b64 s[16:17], -1, 0
	s_cbranch_execz .LBB0_225
	s_branch .LBB0_226

; __global__ void __launch_bounds__(256, 2) hybrid_fwd(Params p) {
;     ...
;     for (int rep = 0; rep < REP_P1; ++rep) phase1(p, l, lds);
;     xcd_barrier(xb);
.LBB0_232:
	s_setprio 0
	v_readlane_b32 s0, v253, 1
	v_readlane_b32 s1, v253, 2
	v_lshlrev_b32_e32 v66, 4, v209
	s_nop 4
	global_load_dwordx4 v[168:171], v66, s[0:1]
	v_add_u32_e32 v66, 0x1000, v66
	global_load_dwordx4 v[172:175], v66, s[0:1]
	v_add_u32_e32 v66, 0x1000, v66
	global_load_dwordx4 v[176:179], v66, s[0:1]
	v_add_u32_e32 v66, 0x1000, v66
	global_load_dwordx4 v[180:183], v66, s[0:1]
	v_add_u32_e32 v66, 0x1000, v66
	global_load_dwordx4 v[184:187], v66, s[0:1]
	v_add_u32_e32 v66, 0x1000, v66
	s_waitcnt vmcnt(0)
	s_mov_b32 s19, s25
